# SEAM 5 flat: write-through stores for y_g / y_r / gate tiles, count-in + poll instead of the two-level barrier with L2 writeback
# baseline (speedup 1.0000x reference)
.LBB0_185:
	s_and_b64 vcc, exec, s[38:39]
	s_cbranch_vccz .LBB0_184
	v_mul_f32_e32 v122, 0xbfb8aa3b, v122
	v_exp_f32_e32 v122, v122
	v_mul_f32_e32 v127, 0xbfb8aa3b, v127
	v_exp_f32_e32 v127, v127
	v_mul_f32_e32 v123, 0xbfb8aa3b, v123
	v_add_f32_e32 v122, 1.0, v122
	v_exp_f32_e32 v123, v123
	v_rcp_f32_e32 v138, v122
	v_add_f32_e32 v122, 1.0, v127
	v_mul_f32_e32 v127, 0xbfb8aa3b, v128
	v_exp_f32_e32 v127, v127
	v_add_f32_e32 v123, 1.0, v123
	v_mul_f32_e32 v124, 0xbfb8aa3b, v124
	v_mul_f32_e32 v126, 0xbfb8aa3b, v126
	v_exp_f32_e32 v124, v124
	v_rcp_f32_e32 v128, v123
	v_add_f32_e32 v123, 1.0, v127
	v_mul_f32_e32 v127, 0xbfb8aa3b, v129
	v_mul_f32_e32 v125, 0xbfb8aa3b, v125
	v_exp_f32_e32 v126, v126
	v_exp_f32_e32 v127, v127
	v_exp_f32_e32 v125, v125
	v_add_f32_e32 v124, 1.0, v124
	v_add_f32_e32 v126, 1.0, v126
	v_rcp_f32_e32 v129, v124
	v_add_f32_e32 v124, 1.0, v127
	v_add_f32_e32 v125, 1.0, v125
	v_mul_f32_e32 v114, 0xbfb8aa3b, v114
	v_rcp_f32_e32 v126, v126
	v_rcp_f32_e32 v122, v122
	v_rcp_f32_e32 v123, v123
	v_rcp_f32_e32 v124, v124
	v_rcp_f32_e32 v125, v125
	v_exp_f32_e32 v114, v114
	v_mul_f32_e32 v119, 0xbfb8aa3b, v119
	v_exp_f32_e32 v119, v119
	s_waitcnt lgkmcnt(0)
	v_ashrrev_i32_e32 v151, 31, v150
	v_lshlrev_b64 v[152:153], 11, v[150:151]
	v_lshl_add_u64 v[152:153], v[148:149], 0, v[152:153]
	v_cvt_pk_bf16_f32 v122, v126, v122
	v_cvt_pk_bf16_f32 v123, v123, v124
	v_cvt_pk_bf16_f32 v124, v138, v128
	v_cvt_pk_bf16_f32 v125, v129, v125
	v_add_f32_e32 v114, 1.0, v114
	v_mul_f32_e32 v115, 0xbfb8aa3b, v115
	global_store_dwordx4 v[152:153], v[122:125], off sc1
	v_exp_f32_e32 v115, v115
	v_mul_f32_e32 v116, 0xbfb8aa3b, v116
	v_rcp_f32_e32 v122, v114
	v_add_f32_e32 v114, 1.0, v119
	v_mul_f32_e32 v119, 0xbfb8aa3b, v120
	v_exp_f32_e32 v119, v119
	v_add_f32_e32 v115, 1.0, v115
	v_mul_f32_e32 v118, 0xbfb8aa3b, v118
	v_exp_f32_e32 v116, v116
	v_rcp_f32_e32 v120, v115
	v_add_f32_e32 v115, 1.0, v119
	v_mul_f32_e32 v119, 0xbfb8aa3b, v121
	v_mul_f32_e32 v117, 0xbfb8aa3b, v117
	v_exp_f32_e32 v118, v118
	v_exp_f32_e32 v119, v119
	v_exp_f32_e32 v117, v117
	v_add_f32_e32 v116, 1.0, v116
	v_add_f32_e32 v118, 1.0, v118
	v_rcp_f32_e32 v121, v116
	v_add_f32_e32 v116, 1.0, v119
	v_add_f32_e32 v117, 1.0, v117
	v_mul_f32_e32 v106, 0xbfb8aa3b, v106
	v_rcp_f32_e32 v118, v118
	v_rcp_f32_e32 v114, v114
	v_rcp_f32_e32 v115, v115
	v_rcp_f32_e32 v116, v116
	v_rcp_f32_e32 v117, v117
	v_exp_f32_e32 v106, v106
	v_mul_f32_e32 v111, 0xbfb8aa3b, v111
	v_exp_f32_e32 v111, v111
	v_cvt_pk_bf16_f32 v114, v118, v114
	v_cvt_pk_bf16_f32 v115, v115, v116
	v_cvt_pk_bf16_f32 v116, v122, v120
	v_cvt_pk_bf16_f32 v117, v121, v117
	v_add_f32_e32 v106, 1.0, v106
	v_mul_f32_e32 v107, 0xbfb8aa3b, v107
	global_store_dwordx4 v[152:153], v[114:117], off offset:256 sc1
	v_exp_f32_e32 v107, v107
	v_mul_f32_e32 v108, 0xbfb8aa3b, v108
	v_rcp_f32_e32 v116, v106
	v_add_f32_e32 v106, 1.0, v111
	v_mul_f32_e32 v111, 0xbfb8aa3b, v112
	v_exp_f32_e32 v111, v111
	v_add_f32_e32 v107, 1.0, v107
	v_mul_f32_e32 v110, 0xbfb8aa3b, v110
	v_exp_f32_e32 v108, v108
	v_rcp_f32_e32 v112, v107
	v_add_f32_e32 v107, 1.0, v111
	v_mul_f32_e32 v111, 0xbfb8aa3b, v113
	v_mul_f32_e32 v109, 0xbfb8aa3b, v109
	v_exp_f32_e32 v110, v110
	v_exp_f32_e32 v111, v111
	v_exp_f32_e32 v109, v109
	v_add_f32_e32 v108, 1.0, v108
	v_add_f32_e32 v110, 1.0, v110
	v_rcp_f32_e32 v113, v108
	v_add_f32_e32 v108, 1.0, v111
	v_add_f32_e32 v109, 1.0, v109
	v_mul_f32_e32 v98, 0xbfb8aa3b, v98
	v_rcp_f32_e32 v110, v110
	v_rcp_f32_e32 v106, v106
	v_rcp_f32_e32 v107, v107
	v_rcp_f32_e32 v108, v108
	v_rcp_f32_e32 v109, v109
	v_exp_f32_e32 v98, v98
	v_mul_f32_e32 v103, 0xbfb8aa3b, v103
	v_or_b32_e32 v114, 16, v150
	v_exp_f32_e32 v103, v103
	v_ashrrev_i32_e32 v115, 31, v114
	v_lshlrev_b64 v[114:115], 11, v[114:115]
	v_lshl_add_u64 v[114:115], v[148:149], 0, v[114:115]
	v_cvt_pk_bf16_f32 v106, v110, v106
	v_cvt_pk_bf16_f32 v107, v107, v108
	v_cvt_pk_bf16_f32 v108, v116, v112
	v_cvt_pk_bf16_f32 v109, v113, v109
	v_add_f32_e32 v98, 1.0, v98
	v_mul_f32_e32 v99, 0xbfb8aa3b, v99
	global_store_dwordx4 v[114:115], v[106:109], off sc1
	v_exp_f32_e32 v99, v99
	v_mul_f32_e32 v100, 0xbfb8aa3b, v100
	v_rcp_f32_e32 v106, v98
	v_add_f32_e32 v98, 1.0, v103
	v_mul_f32_e32 v103, 0xbfb8aa3b, v104
	v_exp_f32_e32 v103, v103
	v_add_f32_e32 v99, 1.0, v99
	v_mul_f32_e32 v102, 0xbfb8aa3b, v102
	v_exp_f32_e32 v100, v100
	v_rcp_f32_e32 v104, v99
	v_add_f32_e32 v99, 1.0, v103
	v_mul_f32_e32 v103, 0xbfb8aa3b, v105
	v_mul_f32_e32 v101, 0xbfb8aa3b, v101
	v_exp_f32_e32 v102, v102
	v_exp_f32_e32 v103, v103
	v_exp_f32_e32 v101, v101
	v_add_f32_e32 v100, 1.0, v100
	v_add_f32_e32 v102, 1.0, v102
	v_rcp_f32_e32 v105, v100
	v_add_f32_e32 v100, 1.0, v103
	v_add_f32_e32 v101, 1.0, v101
	v_mul_f32_e32 v90, 0xbfb8aa3b, v90
	v_rcp_f32_e32 v102, v102
	v_rcp_f32_e32 v98, v98
	v_rcp_f32_e32 v99, v99
	v_rcp_f32_e32 v100, v100
	v_rcp_f32_e32 v101, v101
	v_exp_f32_e32 v90, v90
	v_mul_f32_e32 v95, 0xbfb8aa3b, v95
	v_exp_f32_e32 v95, v95
	v_cvt_pk_bf16_f32 v98, v102, v98
	v_cvt_pk_bf16_f32 v99, v99, v100
	v_cvt_pk_bf16_f32 v100, v106, v104
	v_cvt_pk_bf16_f32 v101, v105, v101
	v_add_f32_e32 v90, 1.0, v90
	v_mul_f32_e32 v91, 0xbfb8aa3b, v91
	global_store_dwordx4 v[114:115], v[98:101], off offset:256 sc1
	v_exp_f32_e32 v91, v91
	v_mul_f32_e32 v92, 0xbfb8aa3b, v92
	v_rcp_f32_e32 v100, v90
	v_add_f32_e32 v90, 1.0, v95
	v_mul_f32_e32 v95, 0xbfb8aa3b, v96
	v_exp_f32_e32 v95, v95
	v_add_f32_e32 v91, 1.0, v91
	v_mul_f32_e32 v94, 0xbfb8aa3b, v94
	v_exp_f32_e32 v92, v92
	v_rcp_f32_e32 v96, v91
	v_add_f32_e32 v91, 1.0, v95
	v_mul_f32_e32 v95, 0xbfb8aa3b, v97
	v_mul_f32_e32 v93, 0xbfb8aa3b, v93
	v_exp_f32_e32 v94, v94
	v_exp_f32_e32 v95, v95
	v_exp_f32_e32 v93, v93
	v_add_f32_e32 v92, 1.0, v92
	v_add_f32_e32 v94, 1.0, v94
	v_rcp_f32_e32 v97, v92
	v_add_f32_e32 v92, 1.0, v95
	v_add_f32_e32 v93, 1.0, v93
	v_mul_f32_e32 v82, 0xbfb8aa3b, v82
	v_rcp_f32_e32 v94, v94
	v_rcp_f32_e32 v90, v90
	v_rcp_f32_e32 v91, v91
	v_rcp_f32_e32 v92, v92
	v_rcp_f32_e32 v93, v93
	v_exp_f32_e32 v82, v82
	v_mul_f32_e32 v87, 0xbfb8aa3b, v87
	v_or_b32_e32 v98, 32, v150
	v_exp_f32_e32 v87, v87
	v_ashrrev_i32_e32 v99, 31, v98
	v_lshlrev_b64 v[98:99], 11, v[98:99]
	v_lshl_add_u64 v[98:99], v[148:149], 0, v[98:99]
	v_cvt_pk_bf16_f32 v90, v94, v90
	v_cvt_pk_bf16_f32 v91, v91, v92
	v_cvt_pk_bf16_f32 v92, v100, v96
	v_cvt_pk_bf16_f32 v93, v97, v93
	v_add_f32_e32 v82, 1.0, v82
	v_mul_f32_e32 v83, 0xbfb8aa3b, v83
	global_store_dwordx4 v[98:99], v[90:93], off sc1
	v_exp_f32_e32 v83, v83
	v_mul_f32_e32 v84, 0xbfb8aa3b, v84
	v_rcp_f32_e32 v90, v82
	v_add_f32_e32 v82, 1.0, v87
	v_mul_f32_e32 v87, 0xbfb8aa3b, v88
	v_exp_f32_e32 v87, v87
	v_add_f32_e32 v83, 1.0, v83
	v_mul_f32_e32 v86, 0xbfb8aa3b, v86
	v_exp_f32_e32 v84, v84
	v_rcp_f32_e32 v88, v83
	v_add_f32_e32 v83, 1.0, v87
	v_mul_f32_e32 v87, 0xbfb8aa3b, v89
	v_mul_f32_e32 v85, 0xbfb8aa3b, v85
	v_exp_f32_e32 v86, v86
	v_exp_f32_e32 v87, v87
	v_exp_f32_e32 v85, v85
	v_add_f32_e32 v84, 1.0, v84
	v_add_f32_e32 v86, 1.0, v86
	v_rcp_f32_e32 v89, v84
	v_add_f32_e32 v84, 1.0, v87
	v_add_f32_e32 v85, 1.0, v85
	v_mul_f32_e32 v74, 0xbfb8aa3b, v74
	v_rcp_f32_e32 v86, v86
	v_rcp_f32_e32 v82, v82
	v_rcp_f32_e32 v83, v83
	v_rcp_f32_e32 v84, v84
	v_rcp_f32_e32 v85, v85
	v_exp_f32_e32 v74, v74
	v_mul_f32_e32 v79, 0xbfb8aa3b, v79
	v_exp_f32_e32 v79, v79
	v_cvt_pk_bf16_f32 v82, v86, v82
	v_cvt_pk_bf16_f32 v83, v83, v84
	v_cvt_pk_bf16_f32 v84, v90, v88
	v_cvt_pk_bf16_f32 v85, v89, v85
	v_add_f32_e32 v74, 1.0, v74
	v_mul_f32_e32 v75, 0xbfb8aa3b, v75
	global_store_dwordx4 v[98:99], v[82:85], off offset:256 sc1
	v_exp_f32_e32 v75, v75
	v_mul_f32_e32 v76, 0xbfb8aa3b, v76
	v_rcp_f32_e32 v84, v74
	v_add_f32_e32 v74, 1.0, v79
	v_mul_f32_e32 v79, 0xbfb8aa3b, v80
	v_exp_f32_e32 v79, v79
	v_add_f32_e32 v75, 1.0, v75
	v_mul_f32_e32 v78, 0xbfb8aa3b, v78
	v_exp_f32_e32 v76, v76
	v_rcp_f32_e32 v80, v75
	v_add_f32_e32 v75, 1.0, v79
	v_mul_f32_e32 v79, 0xbfb8aa3b, v81
	v_mul_f32_e32 v77, 0xbfb8aa3b, v77
	v_exp_f32_e32 v78, v78
	v_exp_f32_e32 v79, v79
	v_exp_f32_e32 v77, v77
	v_add_f32_e32 v76, 1.0, v76
	v_add_f32_e32 v78, 1.0, v78
	v_rcp_f32_e32 v81, v76
	v_add_f32_e32 v76, 1.0, v79
	v_add_f32_e32 v77, 1.0, v77
	v_mul_f32_e32 v66, 0xbfb8aa3b, v66
	v_rcp_f32_e32 v78, v78
	v_rcp_f32_e32 v74, v74
	v_rcp_f32_e32 v75, v75
	v_rcp_f32_e32 v76, v76
	v_rcp_f32_e32 v77, v77
	v_exp_f32_e32 v66, v66
	v_mul_f32_e32 v71, 0xbfb8aa3b, v71
	v_or_b32_e32 v82, 48, v150
	v_exp_f32_e32 v71, v71
	v_ashrrev_i32_e32 v83, 31, v82
	v_lshlrev_b64 v[82:83], 11, v[82:83]
	v_lshl_add_u64 v[82:83], v[148:149], 0, v[82:83]
	v_cvt_pk_bf16_f32 v74, v78, v74
	v_cvt_pk_bf16_f32 v75, v75, v76
	v_cvt_pk_bf16_f32 v76, v84, v80
	v_cvt_pk_bf16_f32 v77, v81, v77
	v_add_f32_e32 v66, 1.0, v66
	v_mul_f32_e32 v67, 0xbfb8aa3b, v67
	global_store_dwordx4 v[82:83], v[74:77], off sc1
	v_exp_f32_e32 v67, v67
	v_mul_f32_e32 v68, 0xbfb8aa3b, v68
	v_rcp_f32_e32 v74, v66
	v_add_f32_e32 v66, 1.0, v71
	v_mul_f32_e32 v71, 0xbfb8aa3b, v72
	v_exp_f32_e32 v71, v71
	v_add_f32_e32 v67, 1.0, v67
	v_mul_f32_e32 v70, 0xbfb8aa3b, v70
	v_exp_f32_e32 v68, v68
	v_rcp_f32_e32 v72, v67
	v_add_f32_e32 v67, 1.0, v71
	v_mul_f32_e32 v71, 0xbfb8aa3b, v73
	v_mul_f32_e32 v69, 0xbfb8aa3b, v69
	v_exp_f32_e32 v70, v70
	v_exp_f32_e32 v71, v71
	v_exp_f32_e32 v69, v69
	v_add_f32_e32 v68, 1.0, v68
	v_add_f32_e32 v70, 1.0, v70
	v_rcp_f32_e32 v73, v68
	v_add_f32_e32 v68, 1.0, v71
	v_add_f32_e32 v69, 1.0, v69
	v_mul_f32_e32 v58, 0xbfb8aa3b, v58
	v_rcp_f32_e32 v70, v70
	v_rcp_f32_e32 v66, v66
	v_rcp_f32_e32 v67, v67
	v_rcp_f32_e32 v68, v68
	v_rcp_f32_e32 v69, v69
	v_exp_f32_e32 v58, v58
	v_mul_f32_e32 v63, 0xbfb8aa3b, v63
	v_exp_f32_e32 v63, v63
	v_cvt_pk_bf16_f32 v66, v70, v66
	v_cvt_pk_bf16_f32 v67, v67, v68
	v_cvt_pk_bf16_f32 v68, v74, v72
	v_cvt_pk_bf16_f32 v69, v73, v69
	v_add_f32_e32 v58, 1.0, v58
	v_mul_f32_e32 v59, 0xbfb8aa3b, v59
	global_store_dwordx4 v[82:83], v[66:69], off offset:256 sc1
	v_exp_f32_e32 v59, v59
	v_mul_f32_e32 v62, 0xbfb8aa3b, v62
	v_rcp_f32_e32 v68, v58
	v_add_f32_e32 v58, 1.0, v63
	v_mul_f32_e32 v63, 0xbfb8aa3b, v64
	v_exp_f32_e32 v63, v63
	v_add_f32_e32 v59, 1.0, v59
	v_mul_f32_e32 v60, 0xbfb8aa3b, v60
	v_exp_f32_e32 v62, v62
	v_exp_f32_e32 v60, v60
	v_rcp_f32_e32 v64, v59
	v_add_f32_e32 v59, 1.0, v63
	v_mul_f32_e32 v63, 0xbfb8aa3b, v65
	v_mul_f32_e32 v61, 0xbfb8aa3b, v61
	v_exp_f32_e32 v63, v63
	v_exp_f32_e32 v61, v61
	v_add_f32_e32 v62, 1.0, v62
	v_add_f32_e32 v60, 1.0, v60
	v_rcp_f32_e32 v62, v62
	v_rcp_f32_e32 v58, v58
	v_rcp_f32_e32 v65, v60
	v_add_f32_e32 v60, 1.0, v63
	v_add_f32_e32 v61, 1.0, v61
	v_mul_f32_e32 v50, 0xbfb8aa3b, v50
	v_rcp_f32_e32 v59, v59
	v_rcp_f32_e32 v60, v60
	v_rcp_f32_e32 v61, v61
	v_exp_f32_e32 v50, v50
	v_mul_f32_e32 v55, 0xbfb8aa3b, v55
	v_exp_f32_e32 v55, v55
	s_mov_b32 s29, 0x40000
	v_cvt_pk_bf16_f32 v58, v62, v58
	v_add_co_u32_e32 v62, vcc, s29, v152
	v_cvt_pk_bf16_f32 v59, v59, v60
	v_cvt_pk_bf16_f32 v60, v68, v64
	v_cvt_pk_bf16_f32 v61, v65, v61
	v_addc_co_u32_e32 v63, vcc, 0, v153, vcc
	v_add_f32_e32 v50, 1.0, v50
	v_mul_f32_e32 v51, 0xbfb8aa3b, v51
	global_store_dwordx4 v[62:63], v[58:61], off sc1
	v_exp_f32_e32 v51, v51
	v_mul_f32_e32 v52, 0xbfb8aa3b, v52
	v_rcp_f32_e32 v58, v50
	v_add_f32_e32 v50, 1.0, v55
	v_mul_f32_e32 v55, 0xbfb8aa3b, v56
	v_exp_f32_e32 v55, v55
	v_add_f32_e32 v51, 1.0, v51
	v_mul_f32_e32 v54, 0xbfb8aa3b, v54
	v_exp_f32_e32 v52, v52
	v_rcp_f32_e32 v56, v51
	v_add_f32_e32 v51, 1.0, v55
	v_mul_f32_e32 v55, 0xbfb8aa3b, v57
	v_mul_f32_e32 v53, 0xbfb8aa3b, v53
	v_exp_f32_e32 v54, v54
	v_exp_f32_e32 v55, v55
	v_exp_f32_e32 v53, v53
	v_add_f32_e32 v52, 1.0, v52
	v_add_f32_e32 v54, 1.0, v54
	v_rcp_f32_e32 v57, v52
	v_add_f32_e32 v52, 1.0, v55
	v_add_f32_e32 v53, 1.0, v53
	v_mul_f32_e32 v42, 0xbfb8aa3b, v42
	v_rcp_f32_e32 v54, v54
	v_rcp_f32_e32 v50, v50
	v_rcp_f32_e32 v51, v51
	v_rcp_f32_e32 v52, v52
	v_rcp_f32_e32 v53, v53
	v_exp_f32_e32 v42, v42
	v_mul_f32_e32 v47, 0xbfb8aa3b, v47
	v_exp_f32_e32 v47, v47
	s_mov_b64 s[38:39], 0x40000
	v_lshl_add_u64 v[66:67], v[152:153], 0, s[38:39]
	v_cvt_pk_bf16_f32 v50, v54, v50
	v_cvt_pk_bf16_f32 v51, v51, v52
	v_cvt_pk_bf16_f32 v52, v58, v56
	v_cvt_pk_bf16_f32 v53, v57, v53
	v_add_f32_e32 v42, 1.0, v42
	v_mul_f32_e32 v43, 0xbfb8aa3b, v43
	global_store_dwordx4 v[66:67], v[50:53], off offset:256 sc1
	v_exp_f32_e32 v43, v43
	v_mul_f32_e32 v46, 0xbfb8aa3b, v46
	v_rcp_f32_e32 v52, v42
	v_add_f32_e32 v42, 1.0, v47
	v_mul_f32_e32 v47, 0xbfb8aa3b, v48
	v_exp_f32_e32 v47, v47
	v_add_f32_e32 v43, 1.0, v43
	v_mul_f32_e32 v44, 0xbfb8aa3b, v44
	v_exp_f32_e32 v46, v46
	v_exp_f32_e32 v44, v44
	v_rcp_f32_e32 v48, v43
	v_add_f32_e32 v43, 1.0, v47
	v_mul_f32_e32 v47, 0xbfb8aa3b, v49
	v_mul_f32_e32 v45, 0xbfb8aa3b, v45
	v_exp_f32_e32 v47, v47
	v_exp_f32_e32 v45, v45
	v_add_f32_e32 v46, 1.0, v46
	v_add_f32_e32 v44, 1.0, v44
	v_rcp_f32_e32 v46, v46
	v_rcp_f32_e32 v42, v42
	v_rcp_f32_e32 v49, v44
	v_add_f32_e32 v44, 1.0, v47
	v_add_f32_e32 v45, 1.0, v45
	v_mul_f32_e32 v34, 0xbfb8aa3b, v34
	v_rcp_f32_e32 v43, v43
	v_rcp_f32_e32 v44, v44
	v_rcp_f32_e32 v45, v45
	v_exp_f32_e32 v34, v34
	v_mul_f32_e32 v39, 0xbfb8aa3b, v39
	v_exp_f32_e32 v39, v39
	s_mov_b32 s29, 0x48000
	v_cvt_pk_bf16_f32 v42, v46, v42
	v_add_co_u32_e32 v46, vcc, s29, v152
	v_cvt_pk_bf16_f32 v43, v43, v44
	v_cvt_pk_bf16_f32 v44, v52, v48
	v_cvt_pk_bf16_f32 v45, v49, v45
	v_addc_co_u32_e32 v47, vcc, 0, v153, vcc
	v_add_f32_e32 v34, 1.0, v34
	v_mul_f32_e32 v35, 0xbfb8aa3b, v35
	global_store_dwordx4 v[46:47], v[42:45], off sc1
	v_exp_f32_e32 v35, v35
	v_mul_f32_e32 v36, 0xbfb8aa3b, v36
	v_rcp_f32_e32 v42, v34
	v_add_f32_e32 v34, 1.0, v39
	v_mul_f32_e32 v39, 0xbfb8aa3b, v40
	v_exp_f32_e32 v39, v39
	v_add_f32_e32 v35, 1.0, v35
	v_mul_f32_e32 v38, 0xbfb8aa3b, v38
	v_exp_f32_e32 v36, v36
	v_rcp_f32_e32 v40, v35
	v_add_f32_e32 v35, 1.0, v39
	v_mul_f32_e32 v39, 0xbfb8aa3b, v41
	v_mul_f32_e32 v37, 0xbfb8aa3b, v37
	v_exp_f32_e32 v38, v38
	v_exp_f32_e32 v39, v39
	v_exp_f32_e32 v37, v37
	v_add_f32_e32 v36, 1.0, v36
	v_add_f32_e32 v38, 1.0, v38
	v_rcp_f32_e32 v41, v36
	v_add_f32_e32 v36, 1.0, v39
	v_add_f32_e32 v37, 1.0, v37
	v_mul_f32_e32 v26, 0xbfb8aa3b, v26
	v_rcp_f32_e32 v38, v38
	v_rcp_f32_e32 v34, v34
	v_rcp_f32_e32 v35, v35
	v_rcp_f32_e32 v36, v36
	v_rcp_f32_e32 v37, v37
	v_exp_f32_e32 v26, v26
	v_mul_f32_e32 v31, 0xbfb8aa3b, v31
	v_exp_f32_e32 v31, v31
	s_mov_b64 s[38:39], 0x48000
	v_lshl_add_u64 v[50:51], v[152:153], 0, s[38:39]
	v_cvt_pk_bf16_f32 v34, v38, v34
	v_cvt_pk_bf16_f32 v35, v35, v36
	v_cvt_pk_bf16_f32 v36, v42, v40
	v_cvt_pk_bf16_f32 v37, v41, v37
	v_add_f32_e32 v26, 1.0, v26
	v_mul_f32_e32 v27, 0xbfb8aa3b, v27
	global_store_dwordx4 v[50:51], v[34:37], off offset:256 sc1
	v_exp_f32_e32 v27, v27
	v_mul_f32_e32 v30, 0xbfb8aa3b, v30
	v_rcp_f32_e32 v36, v26
	v_add_f32_e32 v26, 1.0, v31
	v_mul_f32_e32 v31, 0xbfb8aa3b, v32
	v_exp_f32_e32 v31, v31
	v_add_f32_e32 v27, 1.0, v27
	v_mul_f32_e32 v28, 0xbfb8aa3b, v28
	v_exp_f32_e32 v30, v30
	v_exp_f32_e32 v28, v28
	v_rcp_f32_e32 v32, v27
	v_add_f32_e32 v27, 1.0, v31
	v_mul_f32_e32 v31, 0xbfb8aa3b, v33
	v_mul_f32_e32 v29, 0xbfb8aa3b, v29
	v_exp_f32_e32 v31, v31
	v_exp_f32_e32 v29, v29
	v_add_f32_e32 v30, 1.0, v30
	v_add_f32_e32 v28, 1.0, v28
	v_rcp_f32_e32 v30, v30
	v_rcp_f32_e32 v26, v26
	v_rcp_f32_e32 v33, v28
	v_add_f32_e32 v28, 1.0, v31
	v_add_f32_e32 v29, 1.0, v29
	v_mul_f32_e32 v18, 0xbfb8aa3b, v18
	v_rcp_f32_e32 v27, v27
	v_rcp_f32_e32 v28, v28
	v_rcp_f32_e32 v29, v29
	v_exp_f32_e32 v18, v18
	v_mul_f32_e32 v23, 0xbfb8aa3b, v23
	v_exp_f32_e32 v23, v23
	s_mov_b32 s29, 0x50000
	v_cvt_pk_bf16_f32 v26, v30, v26
	v_add_co_u32_e32 v30, vcc, s29, v152
	v_cvt_pk_bf16_f32 v27, v27, v28
	v_cvt_pk_bf16_f32 v28, v36, v32
	v_cvt_pk_bf16_f32 v29, v33, v29
	v_addc_co_u32_e32 v31, vcc, 0, v153, vcc
	v_add_f32_e32 v18, 1.0, v18
	v_mul_f32_e32 v19, 0xbfb8aa3b, v19
	global_store_dwordx4 v[30:31], v[26:29], off sc1
	v_exp_f32_e32 v19, v19
	v_mul_f32_e32 v20, 0xbfb8aa3b, v20
	v_rcp_f32_e32 v26, v18
	v_add_f32_e32 v18, 1.0, v23
	v_mul_f32_e32 v23, 0xbfb8aa3b, v24
	v_exp_f32_e32 v23, v23
	v_add_f32_e32 v19, 1.0, v19
	v_mul_f32_e32 v22, 0xbfb8aa3b, v22
	v_exp_f32_e32 v20, v20
	v_rcp_f32_e32 v24, v19
	v_add_f32_e32 v19, 1.0, v23
	v_mul_f32_e32 v23, 0xbfb8aa3b, v25
	v_mul_f32_e32 v21, 0xbfb8aa3b, v21
	v_exp_f32_e32 v22, v22
	v_exp_f32_e32 v23, v23
	v_exp_f32_e32 v21, v21
	v_add_f32_e32 v20, 1.0, v20
	v_add_f32_e32 v22, 1.0, v22
	v_rcp_f32_e32 v25, v20
	v_add_f32_e32 v20, 1.0, v23
	v_add_f32_e32 v21, 1.0, v21
	v_mul_f32_e32 v10, 0xbfb8aa3b, v10
	v_rcp_f32_e32 v22, v22
	v_rcp_f32_e32 v18, v18
	v_rcp_f32_e32 v19, v19
	v_rcp_f32_e32 v20, v20
	v_rcp_f32_e32 v21, v21
	v_exp_f32_e32 v10, v10
	v_mul_f32_e32 v15, 0xbfb8aa3b, v15
	v_exp_f32_e32 v15, v15
	s_mov_b64 s[38:39], 0x50000
	v_lshl_add_u64 v[34:35], v[152:153], 0, s[38:39]
	v_cvt_pk_bf16_f32 v18, v22, v18
	v_cvt_pk_bf16_f32 v19, v19, v20
	v_cvt_pk_bf16_f32 v20, v26, v24
	v_cvt_pk_bf16_f32 v21, v25, v21
	v_add_f32_e32 v10, 1.0, v10
	v_mul_f32_e32 v11, 0xbfb8aa3b, v11
	global_store_dwordx4 v[34:35], v[18:21], off offset:256 sc1
	v_exp_f32_e32 v11, v11
	v_mul_f32_e32 v14, 0xbfb8aa3b, v14
	v_rcp_f32_e32 v20, v10
	v_add_f32_e32 v10, 1.0, v15
	v_mul_f32_e32 v15, 0xbfb8aa3b, v16
	v_exp_f32_e32 v15, v15
	v_add_f32_e32 v11, 1.0, v11
	v_mul_f32_e32 v12, 0xbfb8aa3b, v12
	v_exp_f32_e32 v14, v14
	v_exp_f32_e32 v12, v12
	v_rcp_f32_e32 v16, v11
	v_add_f32_e32 v11, 1.0, v15
	v_mul_f32_e32 v15, 0xbfb8aa3b, v17
	v_mul_f32_e32 v13, 0xbfb8aa3b, v13
	v_exp_f32_e32 v15, v15
	v_exp_f32_e32 v13, v13
	v_add_f32_e32 v14, 1.0, v14
	v_add_f32_e32 v12, 1.0, v12
	v_rcp_f32_e32 v14, v14
	v_rcp_f32_e32 v10, v10
	v_rcp_f32_e32 v17, v12
	v_add_f32_e32 v12, 1.0, v15
	v_add_f32_e32 v13, 1.0, v13
	v_mul_f32_e32 v2, 0xbfb8aa3b, v2
	v_rcp_f32_e32 v11, v11
	v_rcp_f32_e32 v12, v12
	v_rcp_f32_e32 v13, v13
	v_exp_f32_e32 v2, v2
	v_mul_f32_e32 v7, 0xbfb8aa3b, v7
	v_exp_f32_e32 v7, v7
	v_cvt_pk_bf16_f32 v10, v14, v10
	v_add_co_u32_e32 v14, vcc, s88, v152
	v_cvt_pk_bf16_f32 v11, v11, v12
	v_cvt_pk_bf16_f32 v12, v20, v16
	v_cvt_pk_bf16_f32 v13, v17, v13
	v_addc_co_u32_e32 v15, vcc, 0, v153, vcc
	v_add_f32_e32 v2, 1.0, v2
	v_mul_f32_e32 v3, 0xbfb8aa3b, v3
	global_store_dwordx4 v[14:15], v[10:13], off sc1
	v_exp_f32_e32 v3, v3
	v_mul_f32_e32 v4, 0xbfb8aa3b, v4
	v_rcp_f32_e32 v10, v2
	v_add_f32_e32 v2, 1.0, v7
	v_mul_f32_e32 v7, 0xbfb8aa3b, v8
	v_exp_f32_e32 v7, v7
	v_add_f32_e32 v3, 1.0, v3
	v_mul_f32_e32 v6, 0xbfb8aa3b, v6
	v_exp_f32_e32 v4, v4
	v_rcp_f32_e32 v8, v3
	v_add_f32_e32 v3, 1.0, v7
	v_mul_f32_e32 v7, 0xbfb8aa3b, v9
	v_mul_f32_e32 v5, 0xbfb8aa3b, v5
	v_exp_f32_e32 v6, v6
	v_exp_f32_e32 v7, v7
	v_exp_f32_e32 v5, v5
	v_add_f32_e32 v4, 1.0, v4
	v_add_f32_e32 v6, 1.0, v6
	v_rcp_f32_e32 v9, v4
	v_add_f32_e32 v4, 1.0, v7
	v_add_f32_e32 v5, 1.0, v5
	v_rcp_f32_e32 v6, v6
	v_rcp_f32_e32 v2, v2
	v_rcp_f32_e32 v3, v3
	v_rcp_f32_e32 v4, v4
	v_rcp_f32_e32 v5, v5
	s_mov_b64 s[38:39], 0x58000
	v_lshl_add_u64 v[18:19], v[152:153], 0, s[38:39]
	v_cvt_pk_bf16_f32 v2, v6, v2
	v_cvt_pk_bf16_f32 v3, v3, v4
	v_cvt_pk_bf16_f32 v4, v10, v8
	v_cvt_pk_bf16_f32 v5, v9, v5
	global_store_dwordx4 v[18:19], v[2:5], off offset:256 sc1
	s_andn2_b64 vcc, exec, s[4:5]
	s_mov_b64 s[4:5], -1
	s_cbranch_vccnz .LBB0_133

.LBB0_290:
	v_or_b32_e32 v34, s0, v104
	v_lshlrev_b32_e32 v34, 2, v34
	global_load_dword v130, v34, s[64:65]
	global_load_dword v132, v34, s[64:65] offset:64
	global_load_dword v134, v34, s[64:65] offset:128
	global_load_dword v136, v34, s[64:65] offset:192
	global_load_dword v74, v34, s[64:65] offset:256
	global_load_dword v72, v34, s[64:65] offset:320
	global_load_dword v70, v34, s[64:65] offset:384
	global_load_dword v68, v34, s[64:65] offset:448
	s_waitcnt lgkmcnt(0)
	s_barrier
	ds_read_u16 v34, v95 offset:34816
	ds_read_u16 v42, v95 offset:35088
	ds_read_u16 v35, v95 offset:35360
	ds_read_u16 v43, v95 offset:35632
	ds_read_u16 v36, v95 offset:35904
	ds_read_u16 v44, v95 offset:36176
	ds_read_u16 v37, v95 offset:36448
	ds_read_u16 v114, v95 offset:43520
	ds_read_u16 v45, v96 offset:34816
	ds_read_u16 v115, v97 offset:34816
	ds_read_u16 v118, v98 offset:34816
	ds_read_u16 v122, v99 offset:34816
	ds_read_u16 v123, v95 offset:62560
	v_add_u32_e32 v146, v79, v91
	ds_read_b128 v[38:41], v146
	s_waitcnt lgkmcnt(5)
	v_perm_b32 v37, v45, v37, s17
	v_perm_b32 v36, v44, v36, s17
	v_perm_b32 v35, v43, v35, s17
	v_perm_b32 v34, v42, v34, s17
	ds_read_u16 v116, v95 offset:43792
	ds_read_u16 v117, v95 offset:44064
	ds_read_u16 v119, v95 offset:44336
	ds_read_u16 v120, v95 offset:44608
	ds_read_u16 v121, v95 offset:44880
	ds_read_u16 v124, v95 offset:45152
	ds_read_u16 v125, v95 offset:52224
	ds_read_u16 v126, v95 offset:52496
	ds_read_b128 v[42:45], v146 offset:64
	s_waitcnt lgkmcnt(9)
	v_mfma_f32_16x16x32_bf16 v[46:49], v[34:37], v[38:41], 0
	s_waitcnt lgkmcnt(3)
	v_perm_b32 v41, v115, v124, s17
	v_perm_b32 v40, v121, v120, s17
	v_perm_b32 v39, v119, v117, s17
	v_perm_b32 v38, v116, v114, s17
	ds_read_u16 v119, v95 offset:52768
	ds_read_u16 v120, v95 offset:53040
	ds_read_u16 v121, v95 offset:53312
	ds_read_u16 v124, v95 offset:53584
	ds_read_u16 v127, v95 offset:53856
	ds_read_u16 v128, v95 offset:60928
	ds_read_u16 v129, v95 offset:61200
	ds_read_u16 v131, v95 offset:61472
	s_waitcnt lgkmcnt(8)
	v_mfma_f32_16x16x32_bf16 v[46:49], v[38:41], v[42:45], v[46:49]
	ds_read_b128 v[114:117], v146 offset:128
	s_waitcnt lgkmcnt(4)
	v_perm_b32 v45, v118, v127, s17
	v_perm_b32 v44, v124, v121, s17
	v_perm_b32 v43, v120, v119, s17
	v_perm_b32 v42, v126, v125, s17
	ds_read_u16 v124, v95 offset:62016
	ds_read_u16 v125, v95 offset:62288
	ds_read_u16 v126, v95 offset:61744
	ds_read_b128 v[118:121], v146 offset:192
	s_waitcnt lgkmcnt(4)
	v_mfma_f32_16x16x32_bf16 v[114:117], v[42:45], v[114:117], v[46:49]
	s_nop 2
	v_perm_b32 v49, v122, v123, s17
	s_waitcnt lgkmcnt(2)
	v_perm_b32 v48, v125, v124, s17
	ds_read_b128 v[122:125], v146 offset:4352
	s_waitcnt lgkmcnt(2)
	v_perm_b32 v47, v126, v131, s17
	v_perm_b32 v46, v129, v128, s17
	v_add_u32_e32 v147, v82, v91
	ds_read_b64 v[138:139], v147
	ds_read_b128 v[126:129], v146 offset:4416
	s_waitcnt lgkmcnt(2)
	v_mfma_f32_16x16x32_bf16 v[122:125], v[34:37], v[122:125], 0
	ds_read_b64 v[140:141], v147 offset:4352
	ds_read_b64 v[142:143], v147 offset:8704
	s_lshl_b32 s8, s0, 1
	s_waitcnt lgkmcnt(3)
	v_lshlrev_b32_e32 v144, 16, v138
	v_mfma_f32_16x16x32_bf16 v[114:117], v[46:49], v[118:121], v[114:117]
	v_and_b32_e32 v145, 0xffff0000, v138
	v_lshlrev_b32_e32 v138, 16, v139
	v_and_b32_e32 v139, 0xffff0000, v139
	s_waitcnt lgkmcnt(2)
	v_mfma_f32_16x16x32_bf16 v[122:125], v[38:41], v[126:129], v[122:125]
	ds_read_b128 v[126:129], v146 offset:4480
	s_add_i32 s18, s18, s3
	s_add_i32 s14, s14, s15
	s_add_i32 s0, s2, s18
	s_cmpk_lt_i32 s0, 0x400
	s_mov_b32 s21, s4
	s_waitcnt vmcnt(7)
	v_pk_add_f32 v[114:115], v[130:131], v[114:115] op_sel_hi:[0,1]
	v_pk_mul_f32 v[114:115], v[114:115], v[144:145]
	v_pk_add_f32 v[130:131], v[130:131], v[116:117] op_sel_hi:[0,1]
	v_cvt_pk_bf16_f32 v144, v114, v115
	ds_read_b128 v[114:117], v146 offset:4544
	s_waitcnt lgkmcnt(1)
	v_mfma_f32_16x16x32_bf16 v[118:121], v[42:45], v[126:129], v[122:125]
	ds_read_b128 v[126:129], v146 offset:8832
	s_waitcnt lgkmcnt(1)
	v_mfma_f32_16x16x32_bf16 v[114:117], v[46:49], v[114:117], v[118:121]
	v_mul_f32_e64 v122, v130, v138
	v_mul_f32_e64 v123, v131, v139
	v_lshlrev_b32_e32 v138, 16, v141
	v_cvt_pk_bf16_f32 v145, v122, v123
	s_nop 0
	ds_read_b128 v[118:121], v146 offset:8704
	v_lshlrev_b32_e32 v122, 16, v140
	v_and_b32_e32 v123, 0xffff0000, v140
	s_waitcnt vmcnt(6)
	v_pk_add_f32 v[114:115], v[132:133], v[114:115] op_sel_hi:[0,1]
	v_pk_mul_f32 v[114:115], v[114:115], v[122:123]
	ds_read_b128 v[122:125], v146 offset:8768
	s_waitcnt lgkmcnt(1)
	v_mfma_f32_16x16x32_bf16 v[118:121], v[34:37], v[118:121], 0
	v_cvt_pk_bf16_f32 v130, v114, v115
	v_and_b32_e32 v139, 0xffff0000, v141
	ds_write_b64 v147, v[144:145]
	s_waitcnt lgkmcnt(1)
	v_mfma_f32_16x16x32_bf16 v[118:121], v[38:41], v[122:125], v[118:121]
	v_add_f32_e64 v122, v132, v116
	v_add_f32_e64 v123, v132, v117
	ds_read_b128 v[114:117], v146 offset:8896
	v_pk_mul_f32 v[122:123], v[122:123], v[138:139]
	v_mfma_f32_16x16x32_bf16 v[118:121], v[42:45], v[126:129], v[118:121]
	v_cvt_pk_bf16_f32 v131, v122, v123
	ds_write_b64 v147, v[130:131] offset:4352
	v_add_u32_e32 v122, v79, v92
	s_waitcnt lgkmcnt(1)
	v_mfma_f32_16x16x32_bf16 v[114:117], v[46:49], v[114:117], v[118:121]
	v_add_u32_e32 v126, v82, v92
	s_nop 1
	v_lshlrev_b32_e32 v118, 16, v142
	v_and_b32_e32 v119, 0xffff0000, v142
	s_waitcnt vmcnt(5)
	s_nop 1
	v_pk_add_f32 v[114:115], v[134:135], v[114:115] op_sel_hi:[0,1]
	v_pk_mul_f32 v[114:115], v[114:115], v[118:119]
	v_lshlrev_b32_e32 v118, 16, v143
	v_and_b32_e32 v119, 0xffff0000, v143
	v_pk_add_f32 v[116:117], v[134:135], v[116:117] op_sel_hi:[0,1]
	v_pk_mul_f32 v[116:117], v[116:117], v[118:119]
	v_cvt_pk_bf16_f32 v114, v114, v115
	v_cvt_pk_bf16_f32 v115, v116, v117
	ds_write_b64 v147, v[114:115] offset:8704
	ds_read_b128 v[114:117], v122
	ds_read_b128 v[118:121], v122 offset:64
	s_waitcnt lgkmcnt(1)
	v_mfma_f32_16x16x32_bf16 v[114:117], v[34:37], v[114:117], 0
	s_waitcnt lgkmcnt(0)
	v_mfma_f32_16x16x32_bf16 v[114:117], v[38:41], v[118:121], v[114:117]
	ds_read_b128 v[118:121], v122 offset:128
	ds_read_b128 v[122:125], v122 offset:192
	s_waitcnt lgkmcnt(1)
	v_mfma_f32_16x16x32_bf16 v[114:117], v[42:45], v[118:121], v[114:117]
	ds_read_b64 v[118:119], v126
	s_waitcnt lgkmcnt(0)
	v_lshlrev_b32_e32 v120, 16, v118
	v_mfma_f32_16x16x32_bf16 v[114:117], v[46:49], v[122:125], v[114:117]
	v_and_b32_e32 v121, 0xffff0000, v118
	v_lshlrev_b32_e32 v118, 16, v119
	v_and_b32_e32 v119, 0xffff0000, v119
	s_waitcnt vmcnt(4)
	s_nop 3
	v_pk_add_f32 v[114:115], v[136:137], v[114:115] op_sel_hi:[0,1]
	v_pk_add_f32 v[116:117], v[136:137], v[116:117] op_sel_hi:[0,1]
	v_pk_mul_f32 v[114:115], v[114:115], v[120:121]
	v_pk_mul_f32 v[116:117], v[116:117], v[118:119]
	v_cvt_pk_bf16_f32 v114, v114, v115
	v_cvt_pk_bf16_f32 v115, v116, v117
	ds_write_b64 v126, v[114:115]
	ds_read_b128 v[114:117], v146 offset:17408
	ds_read_b128 v[118:121], v146 offset:17472
	s_waitcnt lgkmcnt(1)
	v_mfma_f32_16x16x32_bf16 v[114:117], v[34:37], v[114:117], 0
	s_waitcnt lgkmcnt(0)
	v_mfma_f32_16x16x32_bf16 v[114:117], v[38:41], v[118:121], v[114:117]
	ds_read_b128 v[118:121], v146 offset:17536
	ds_read_b128 v[122:125], v146 offset:17600
	ds_read_b64 v[130:131], v147 offset:17408
	ds_read_b64 v[132:133], v147 offset:21760
	ds_read_b64 v[134:135], v147 offset:26112
	s_waitcnt lgkmcnt(4)
	v_mfma_f32_16x16x32_bf16 v[114:117], v[42:45], v[118:121], v[114:117]
	ds_read_b128 v[118:121], v146 offset:21760
	ds_read_b128 v[126:129], v146 offset:21888
	s_waitcnt lgkmcnt(4)
	v_lshlrev_b32_e32 v136, 16, v131
	v_mfma_f32_16x16x32_bf16 v[114:117], v[46:49], v[122:125], v[114:117]
	v_lshlrev_b32_e32 v122, 16, v130
	v_and_b32_e32 v123, 0xffff0000, v130
	v_and_b32_e32 v137, 0xffff0000, v131
	s_waitcnt vmcnt(3)
	s_nop 3
	v_pk_add_f32 v[114:115], v[74:75], v[114:115] op_sel_hi:[0,1]
	v_pk_mul_f32 v[114:115], v[114:115], v[122:123]
	ds_read_b128 v[122:125], v146 offset:21824
	s_waitcnt lgkmcnt(2)
	v_mfma_f32_16x16x32_bf16 v[118:121], v[34:37], v[118:121], 0
	v_cvt_pk_bf16_f32 v130, v114, v115
	s_waitcnt lgkmcnt(0)
	v_mfma_f32_16x16x32_bf16 v[118:121], v[38:41], v[122:125], v[118:121]
	v_add_f32_e64 v122, v74, v116
	v_add_f32_e64 v123, v74, v117
	ds_read_b128 v[114:117], v146 offset:21952
	v_pk_mul_f32 v[122:123], v[122:123], v[136:137]
	v_mfma_f32_16x16x32_bf16 v[118:121], v[42:45], v[126:129], v[118:121]
	v_cvt_pk_bf16_f32 v131, v122, v123
	v_lshlrev_b32_e32 v122, 16, v132
	v_and_b32_e32 v123, 0xffff0000, v132
	s_waitcnt lgkmcnt(0)
	v_mfma_f32_16x16x32_bf16 v[114:117], v[46:49], v[114:117], v[118:121]
	ds_read_b128 v[126:129], v146 offset:26240
	ds_write_b64 v147, v[130:131] offset:17408
	v_lshlrev_b32_e32 v132, 16, v133
	ds_read_b128 v[118:121], v146 offset:26112
	v_and_b32_e32 v133, 0xffff0000, v133
	s_waitcnt vmcnt(2)
	s_nop 1
	v_pk_add_f32 v[114:115], v[72:73], v[114:115] op_sel_hi:[0,1]
	v_pk_mul_f32 v[114:115], v[114:115], v[122:123]
	ds_read_b128 v[122:125], v146 offset:26176
	s_waitcnt lgkmcnt(1)
	v_mfma_f32_16x16x32_bf16 v[118:121], v[34:37], v[118:121], 0
	v_cvt_pk_bf16_f32 v130, v114, v115
	s_waitcnt lgkmcnt(0)
	v_mfma_f32_16x16x32_bf16 v[118:121], v[38:41], v[122:125], v[118:121]
	v_add_f32_e64 v122, v72, v116
	v_add_f32_e64 v123, v72, v117
	ds_read_b128 v[114:117], v146 offset:26304
	v_pk_mul_f32 v[122:123], v[122:123], v[132:133]
	v_mfma_f32_16x16x32_bf16 v[118:121], v[42:45], v[126:129], v[118:121]
	v_cvt_pk_bf16_f32 v131, v122, v123
	ds_write_b64 v147, v[130:131] offset:21760
	s_waitcnt lgkmcnt(1)
	v_mfma_f32_16x16x32_bf16 v[114:117], v[46:49], v[114:117], v[118:121]
	s_nop 3
	v_lshlrev_b32_e32 v118, 16, v134
	v_and_b32_e32 v119, 0xffff0000, v134
	s_waitcnt vmcnt(1)
	s_nop 0
	v_pk_add_f32 v[114:115], v[70:71], v[114:115] op_sel_hi:[0,1]
	v_pk_mul_f32 v[114:115], v[114:115], v[118:119]
	v_lshlrev_b32_e32 v118, 16, v135
	v_and_b32_e32 v119, 0xffff0000, v135
	v_pk_add_f32 v[116:117], v[70:71], v[116:117] op_sel_hi:[0,1]
	v_pk_mul_f32 v[116:117], v[116:117], v[118:119]
	v_cvt_pk_bf16_f32 v114, v114, v115
	v_cvt_pk_bf16_f32 v115, v116, v117
	ds_write_b64 v147, v[114:115] offset:26112
	v_add_u32_e32 v70, v79, v93
	ds_read_b128 v[114:117], v70
	ds_read_b128 v[118:121], v70 offset:64
	s_waitcnt lgkmcnt(1)
	v_mfma_f32_16x16x32_bf16 v[34:37], v[34:37], v[114:117], 0
	s_waitcnt lgkmcnt(0)
	v_mfma_f32_16x16x32_bf16 v[34:37], v[38:41], v[118:121], v[34:37]
	ds_read_b128 v[38:41], v70 offset:128
	ds_read_b128 v[114:117], v70 offset:192
	s_waitcnt lgkmcnt(1)
	v_mfma_f32_16x16x32_bf16 v[34:37], v[42:45], v[38:41], v[34:37]
	v_add_u32_e32 v42, v82, v93
	ds_read_b64 v[38:39], v42
	s_waitcnt lgkmcnt(0)
	v_lshlrev_b32_e32 v40, 16, v38
	v_mfma_f32_16x16x32_bf16 v[34:37], v[46:49], v[114:117], v[34:37]
	v_and_b32_e32 v41, 0xffff0000, v38
	v_lshlrev_b32_e32 v38, 16, v39
	v_and_b32_e32 v39, 0xffff0000, v39
	v_lshl_add_u64 v[46:47], v[54:55], 0, s[8:9]
	s_waitcnt vmcnt(0)
	s_nop 2
	v_pk_add_f32 v[34:35], v[68:69], v[34:35] op_sel_hi:[0,1]
	v_pk_add_f32 v[36:37], v[68:69], v[36:37] op_sel_hi:[0,1]
	v_pk_mul_f32 v[34:35], v[34:35], v[40:41]
	v_pk_mul_f32 v[36:37], v[36:37], v[38:39]
	v_cvt_pk_bf16_f32 v34, v34, v35
	v_cvt_pk_bf16_f32 v35, v36, v37
	ds_write_b64 v42, v[34:35]
	s_waitcnt lgkmcnt(0)
	s_barrier
	ds_read_b128 v[34:37], v107
	v_lshlrev_b64 v[38:39], 12, v[66:67]
	v_lshl_add_u64 v[48:49], v[46:47], 0, v[38:39]
	ds_read_b128 v[38:41], v108
	ds_read_b128 v[42:45], v107 offset:17408
	s_waitcnt lgkmcnt(2)
	global_store_dwordx4 v[48:49], v[34:37], off sc1
	s_nop 1
	v_lshlrev_b64 v[34:35], 12, v[64:65]
	v_lshl_add_u64 v[48:49], v[46:47], 0, v[34:35]
	s_waitcnt lgkmcnt(1)
	global_store_dwordx4 v[48:49], v[38:41], off sc1
	ds_read_b128 v[34:37], v109
	s_nop 0
	v_or_b32_e32 v38, s20, v87
	v_ashrrev_i32_e32 v39, 31, v38
	v_lshlrev_b64 v[38:39], 12, v[38:39]
	v_lshl_add_u64 v[38:39], v[46:47], 0, v[38:39]
	s_waitcnt lgkmcnt(1)
	global_store_dwordx4 v[38:39], v[42:45], off sc1
	v_lshlrev_b64 v[38:39], 12, v[62:63]
	v_lshl_add_u64 v[38:39], v[46:47], 0, v[38:39]
	s_waitcnt lgkmcnt(0)
	global_store_dwordx4 v[38:39], v[34:37], off sc1
	s_cbranch_scc0 .LBB0_299

.LBB0_505:
	s_or_b64 exec, exec, s[66:67]
	v_add_f32_e32 v44, 0, v66
	v_add_f32_e32 v47, 0, v67
	v_add_f32_e32 v49, 0, v68
	v_add_f32_e32 v44, v44, v45
	v_add_f32_e32 v45, 0, v70
	v_add_f32_e32 v43, 0, v142
	v_add_f32_e32 v48, v49, v48
	v_add_f32_e32 v46, v47, v46
	v_add_f32_e32 v47, 0, v71
	v_add_f32_e32 v49, 0, v72
	v_add_f32_e32 v45, v45, v54
	v_add_f32_e32 v54, 0, v61
	v_add_f32_e32 v42, v43, v42
	v_add_f32_e32 v43, 0, v76
	v_add_f32_e32 v49, v49, v56
	v_add_f32_e32 v47, v47, v55
	v_add_f32_e32 v50, 0, v53
	v_add_f32_e32 v51, 0, v57
	v_add_f32_e32 v52, 0, v74
	v_add_f32_e32 v53, 0, v75
	v_add_f32_e32 v55, 0, v65
	v_add_f32_e32 v56, 0, v69
	v_add_f32_e32 v57, 0, v73
	v_add_f32_e32 v54, v54, v153
	v_add_f32_e32 v43, v43, v194
	v_add_f32_e32 v53, v53, v60
	v_add_f32_e32 v52, v52, v59
	v_add_f32_e32 v51, v51, v58
	v_add_f32_e32 v50, v50, v174
	v_add_f32_e32 v57, v57, v64
	v_add_f32_e32 v56, v56, v63
	v_add_f32_e32 v55, v55, v62
	ds_write_b32 v122, v54 offset:51200
	ds_write_b32 v123, v55 offset:51200
	ds_write_b32 v124, v56 offset:51200
	ds_write_b32 v125, v57 offset:51200
	ds_write_b32 v127, v50 offset:51200
	ds_write_b32 v128, v51 offset:51200
	ds_write_b32 v129, v52 offset:51200
	ds_write_b32 v130, v53 offset:51200
	ds_write_b32 v131, v43 offset:51200
	ds_write_b32 v132, v45 offset:51200
	ds_write_b32 v133, v47 offset:51200
	ds_write_b32 v134, v49 offset:51200
	ds_write_b32 v135, v42 offset:51200
	ds_write_b32 v136, v44 offset:51200
	ds_write_b32 v137, v46 offset:51200
	ds_write_b32 v138, v48 offset:51200
	ds_read_b128 v[42:45], v120 offset:51200
	ds_read_b128 v[46:49], v120 offset:51216
	s_waitcnt vmcnt(1)
	v_lshlrev_b32_e32 v50, 16, v38
	v_and_b32_e32 v51, 0xffff0000, v38
	s_add_i32 s85, s85, 16
	s_waitcnt lgkmcnt(1)
	v_pk_mul_f32 v[42:43], v[42:43], v[50:51]
	s_add_i32 s61, s61, 8
	v_cvt_pk_bf16_f32 v38, v42, v43
	v_lshlrev_b32_e32 v42, 16, v39
	v_and_b32_e32 v43, 0xffff0000, v39
	v_pk_mul_f32 v[42:43], v[44:45], v[42:43]
	s_addk_i32 s78, 0x200
	v_cvt_pk_bf16_f32 v39, v42, v43
	v_lshlrev_b32_e32 v42, 16, v40
	v_and_b32_e32 v43, 0xffff0000, v40
	s_waitcnt lgkmcnt(0)
	v_pk_mul_f32 v[42:43], v[46:47], v[42:43]
	s_waitcnt vmcnt(0)
	v_lshlrev_b32_e32 v46, 16, v34
	v_cvt_pk_bf16_f32 v40, v42, v43
	v_lshlrev_b32_e32 v42, 16, v41
	v_and_b32_e32 v43, 0xffff0000, v41
	v_pk_mul_f32 v[42:43], v[48:49], v[42:43]
	v_and_b32_e32 v47, 0xffff0000, v34
	v_cvt_pk_bf16_f32 v41, v42, v43
	ds_read_b128 v[42:45], v121 offset:51200
	global_store_dwordx4 v[104:105], v[38:41], off sc1
	ds_read_b128 v[38:41], v121 offset:51216
	s_mov_b64 s[50:51], -1
	s_cmp_lg_u32 s78, 0
	s_waitcnt lgkmcnt(1)
	v_pk_mul_f32 v[42:43], v[42:43], v[46:47]
	s_mov_b32 s67, s86
	v_cvt_pk_bf16_f32 v34, v42, v43
	v_lshlrev_b32_e32 v42, 16, v35
	v_and_b32_e32 v43, 0xffff0000, v35
	v_pk_mul_f32 v[42:43], v[44:45], v[42:43]
	s_nop 0
	v_cvt_pk_bf16_f32 v35, v42, v43
	v_lshlrev_b32_e32 v42, 16, v36
	v_and_b32_e32 v43, 0xffff0000, v36
	s_waitcnt lgkmcnt(0)
	v_pk_mul_f32 v[38:39], v[38:39], v[42:43]
	s_nop 0
	v_cvt_pk_bf16_f32 v36, v38, v39
	v_lshlrev_b32_e32 v38, 16, v37
	v_and_b32_e32 v39, 0xffff0000, v37
	v_pk_mul_f32 v[38:39], v[40:41], v[38:39]
	s_nop 0
	v_cvt_pk_bf16_f32 v37, v38, v39
	global_store_dwordx4 v[102:103], v[34:37], off sc1
	s_cbranch_scc0 .LBB0_556

.LBB0_556:
	s_cmp_gt_i32 s95, 6
	s_cselect_b64 s[0:1], -1, 0
	s_and_b64 s[4:5], s[58:59], s[0:1]
	s_andn2_b64 vcc, exec, s[4:5]
	s_cbranch_vccnz .LBB0_610
	s_waitcnt vmcnt(0) lgkmcnt(0)
	s_barrier
	s_mov_b64 s[4:5], exec
	v_readlane_b32 s6, v246, 2
	v_readlane_b32 s7, v246, 3
	s_and_b64 s[6:7], s[4:5], s[6:7]
	s_mov_b64 exec, s[6:7]
	s_cbranch_execz .Ls5_end
	buffer_inv sc1
	s_add_u32 s6, s92, 0x55100
	s_addc_u32 s7, s93, 0
	v_mov_b32_e32 v2, 0
	v_mov_b32_e32 v3, 1
	global_atomic_add v2, v3, s[6:7]
	s_mov_b32 s10, 0x400000
	s_movk_i32 s11, 0xff
.Ls5_poll:
	global_load_dword v3, v2, s[6:7] sc1
	s_waitcnt vmcnt(0)
	v_cmp_lt_u32_e32 vcc, s11, v3
	s_cbranch_vccnz .Ls5_end
	s_sleep 1
	s_sub_u32 s10, s10, 1
	s_cmp_lg_u32 s10, 0
	s_cbranch_scc1 .Ls5_poll
.Ls5_end:
	s_mov_b64 exec, s[4:5]
	s_barrier
.LBB0_610:
	s_cmp_lt_i32 s94, 7
	s_cselect_b64 s[4:5], -1, 0
	s_and_b64 s[4:5], s[4:5], s[0:1]
	s_andn2_b64 vcc, exec, s[4:5]
	s_cbranch_vccnz .LBB0_629
	s_cmpk_gt_i32 s2, 0xff
	v_readfirstlane_b32 s46, v0
	s_cbranch_scc1 .LBB0_629
	s_waitcnt vmcnt(0)
	v_lshrrev_b32_e32 v4, 1, v0
	v_and_b32_e32 v14, 24, v4
	v_lshrrev_b32_e32 v4, 5, v0
	s_add_u32 s47, s92, 0x8000000
	v_lshlrev_b32_e32 v1, 4, v0
	v_and_b32_e32 v2, 32, v0
	v_and_b32_e32 v4, 4, v4
	v_bfe_u32 v5, v0, 2, 2
	s_addc_u32 s50, s93, 0
	v_bfe_u32 v13, v0, 2, 4
	v_bitop3_b32 v3, v1, v2, 48 bitop3:0x6c
	v_and_b32_e32 v12, 64, v0
	v_or3_b32 v4, v4, v5, v14
	v_lshrrev_b32_e32 v5, 3, v0
	v_or_b32_e32 v15, 0x2000, v1
	s_add_u32 s51, s92, 0x2200000
	v_or_b32_e32 v2, v3, v12
	v_and_or_b32 v6, v5, 48, v13
	v_and_or_b32 v5, v5, 32, v4
	v_lshrrev_b32_e32 v1, 7, v15
	s_movk_i32 s0, 0x70
	s_addc_u32 s58, s93, 0
	v_lshl_or_b32 v166, v5, 12, v2
	v_and_or_b32 v5, v1, s0, v13
	s_movk_i32 s0, 0x60
	s_ashr_i32 s60, s2, 31
	v_and_or_b32 v1, v1, s0, v4
	s_lshr_b32 s0, s60, 29
	s_add_i32 s0, s2, s0
	s_and_b32 s6, s0, -8
	s_lshr_b32 s12, s46, 6
	s_sub_i32 s6, s2, s6
	s_lshr_b32 s1, s46, 8
	s_lshl_b32 s59, s12, 10
	s_lshl_b32 s8, s6, 5
	s_ashr_i32 s0, s0, 3
	s_mul_i32 s7, s6, 33
	s_cmp_lt_i32 s6, 0
	s_cselect_b32 s6, s7, s8
	s_add_i32 s0, s6, s0
	s_ashr_i32 s6, s0, 31
	s_lshr_b32 s6, s6, 27
	s_add_i32 s6, s0, s6
	s_ashr_i32 s7, s6, 5
	s_andn2_b32 s6, s6, 31
	s_sub_i32 s6, s0, s6
	s_bfe_i32 s0, s6, 0x80000
	s_bfe_u32 s0, s0, 0x3000c
	s_add_i32 s8, s6, s0
	s_bfe_i32 s0, s8, 0x80000
	s_and_b32 s8, s8, 0xf8
	s_sub_i32 s6, s6, s8
	s_lshl_b32 s7, s7, 3
	s_sext_i32_i16 s0, s0
	s_sext_i32_i8 s6, s6
	s_lshr_b32 s0, s0, 3
	s_add_i32 s40, s7, s6
	s_ashr_i32 s41, s40, 31
	s_bfe_i64 s[8:9], s[0:1], 0x100000
	s_lshl_b64 s[6:7], s[40:41], 20
	s_lshl_b64 s[8:9], s[8:9], 20
	s_add_u32 s42, s51, s8
	s_addc_u32 s43, s58, s9
	s_add_i32 s61, s59, 0
	s_add_i32 m0, s61, 0x10000
	v_lshl_or_b32 v170, v1, 12, v2
	global_load_lds_dwordx4 v166, s[42:43]
	s_add_i32 m0, s61, 0x12000
	s_add_u32 s8, s42, 0x80000
	global_load_lds_dwordx4 v170, s[42:43]
	s_addc_u32 s9, s43, 0
	s_add_i32 m0, s61, 0x14000
	v_lshl_or_b32 v164, v6, 12, v2
	global_load_lds_dwordx4 v166, s[8:9]
	s_add_i32 m0, s61, 0x16000
	s_add_u32 s38, s47, s6
	s_addc_u32 s39, s50, s7
	s_add_i32 s62, s61, 0x2000
	global_load_lds_dwordx4 v170, s[8:9]
	s_mov_b32 m0, s61
	s_add_u32 s6, s38, 0x80000
	v_lshl_or_b32 v168, v5, 12, v2
	global_load_lds_dwordx4 v164, s[38:39]
	s_mov_b32 m0, s62
	s_addc_u32 s7, s39, 0
	s_add_i32 s63, s61, 0x4000
	global_load_lds_dwordx4 v168, s[38:39]
	s_mov_b32 m0, s63
	s_add_i32 s64, s61, 0x6000
	global_load_lds_dwordx4 v164, s[6:7]
	s_mov_b32 m0, s64
	v_mov_b32_e32 v2, 0
	global_load_lds_dwordx4 v168, s[6:7]
	v_mov_b32_e32 v167, v2
	v_mov_b32_e32 v171, v2
	v_mov_b32_e32 v165, v2
	v_mov_b32_e32 v169, v2
	s_mov_b32 s65, 0
	v_lshl_add_u64 v[10:11], s[42:43], 0, v[166:167]
	v_lshl_add_u64 v[8:9], s[42:43], 0, v[170:171]
	v_lshl_add_u64 v[6:7], s[38:39], 0, v[164:165]
	s_cmp_lg_u32 s1, 1
	v_lshl_add_u64 v[4:5], s[38:39], 0, v[168:169]
	s_cbranch_scc1 .LBB0_614
	s_barrier
